# live out-proj tile epilogue: gate vector loaded once per half instead of a dependent load before each of the 16 stores, per-store vmcnt(0) waits removed
# speedup vs baseline: 1.0123x; 1.0033x over previous
; template <int TJ>
; DI void outproj_tile(const Params& p, int l, char* smem, int b, int trow0, int n0) {
;     ...
;     const float* gt = p.mod + ((size_t)l * 9 + (trow0 < SEQ ? b : 8)) * 3072 + 2048 + n0 + 64 * wf;
;     const float* xs = src_row(p, l, b, trow0 + 32 * TJ * wt) + n0 + 64 * wf;
;     float* xd = dst_row(p, b, trow0 + 32 * TJ * wt) + n0 + 64 * wf;
;     char* sb = smem + wave * 8192;
;     float4 xo[2][4 * TJ];
; #pragma unroll
;     for (int i = 0; i < 2; ++i)
; #pragma unroll
;         for (int it = 0; it < 4 * TJ; ++it) {
;             const int c = lane + 64 * it, row = c >> 3, f = 32 * i + 4 * ((c & 7) ^ (row & 7));
;             xo[i][it] = *(const float4*)(xs + (size_t)row * D + f);
;         }
; #pragma unroll
;     for (int i = 0; i < 2; ++i) {
; #pragma unroll
;         for (int j = 0; j < TJ; ++j)
; #pragma unroll
;             for (int q = 0; q < 4; ++q) {
;                 const int row = 32 * j + r, c16 = 2 * q + h;
;                 float4 y; y.x = acc[i][j][4 * q]; y.y = acc[i][j][4 * q + 1]; y.z = acc[i][j][4 * q + 2]; y.w = acc[i][j][4 * q + 3];
;                 *(float4*)(sb + row * 128 + ((c16 ^ (row & 7)) << 4)) = y;
.LBB0_38:
	global_load_dwordx2 v[64:65], v[64:65], off
	s_load_dwordx4 s[44:47], s[0:1], 0xa8
	v_lshlrev_b64 v[68:69], 12, v[68:69]
	s_cmpk_lt_u32 s28, 0x800
	v_readlane_b32 s28, v255, 17
	v_readlane_b32 s29, v255, 18
	v_ashrrev_i32_e32 v67, 31, v66
	v_cndmask_b32_e64 v67, 0, v67, s[40:41]
	v_and_b32_e32 v118, 63, v116
	v_or_b32_e32 v117, 64, v118
	v_mov_b32_e32 v73, v193
	v_or_b32_e32 v120, 0x80, v118
	v_lshlrev_b32_e32 v122, 7, v116
	v_and_b32_e32 v123, 0xffffe000, v122
	v_mov_b32_e32 v77, v193
	v_or_b32_e32 v121, 0xc0, v118
	v_or_b32_e32 v124, 0x100, v118
	v_or_b32_e32 v125, 0x140, v118
	v_or_b32_e32 v148, 0x180, v118
	v_or_b32_e32 v160, 0x1c0, v118
	v_bfe_u32 v119, v116, 5, 1
	v_lshrrev_b32_e32 v84, 3, v124
	v_lshrrev_b32_e32 v90, 3, v125
	v_lshrrev_b32_e32 v98, 3, v148
	v_lshrrev_b32_e32 v110, 3, v160
	v_add_u32_e32 v161, 32, v123
	v_and_b32_e32 v122, 0xf80, v122
	v_xor_b32_e32 v88, v84, v116
	v_xor_b32_e32 v92, v90, v116
	v_xor_b32_e32 v102, v98, v116
	v_xor_b32_e32 v126, v110, v116
	v_add_u32_e32 v122, v161, v122
	v_and_b32_e32 v123, 7, v116
	s_cselect_b32 s4, s28, 8
	s_mul_i32 s5, s60, 9
	s_add_u32 s4, s5, s4
	s_mul_hi_i32 s5, s60, 9
	s_addc_u32 s5, s5, 0
	s_mulk_i32 s5, 0x3000
	s_mul_hi_u32 s6, s4, 0x3000
	s_add_i32 s6, s6, s5
	s_mulk_i32 s4, 0x3000
	s_waitcnt lgkmcnt(0)
	s_add_u32 s4, s52, s4
	s_addc_u32 s5, s53, s6
	s_add_u32 s4, s4, s74
	v_mov_b32_e32 v83, v193
	v_lshlrev_b32_e32 v84, 12, v84
	v_mov_b32_e32 v85, v193
	v_lshlrev_b32_e32 v88, 4, v88
	s_addc_u32 s5, s5, 0
	v_and_b32_e32 v88, 0x70, v88
	v_mov_b32_e32 v89, v193
	v_lshlrev_b32_e32 v90, 12, v90
	v_mov_b32_e32 v91, v193
	v_lshlrev_b32_e32 v92, 4, v92
	v_lshlrev_b32_e32 v98, 12, v98
	v_mov_b32_e32 v99, v193
	v_lshlrev_b32_e32 v110, 12, v110
	v_mov_b32_e32 v111, v193
	v_and_b32_e32 v92, 0x70, v92
	v_mov_b32_e32 v93, v193
	v_lshlrev_b32_e32 v102, 4, v102
	v_and_b32_e32 v102, 0x70, v102
	v_mov_b32_e32 v103, v193
	v_lshl_add_u32 v156, v124, 4, v161
	v_lshl_add_u32 v152, v125, 4, v161
	v_lshl_add_u32 v159, v117, 4, v161
	v_lshl_add_u32 v158, v120, 4, v161
	v_lshl_add_u32 v157, v121, 4, v161
	v_lshl_add_u32 v155, v118, 4, v161
	v_lshl_add_u32 v149, v148, 4, v161
	v_lshl_add_u32 v148, v160, 4, v161
	s_movk_i32 s6, 0x400
	s_and_b64 vcc, exec, s[62:63]
	s_waitcnt vmcnt(0)
	v_lshl_add_u64 v[70:71], v[64:65], 0, v[70:71]
	v_and_b32_e32 v64, 64, v116
	v_lshl_add_u64 v[68:69], v[70:71], 0, v[68:69]
	v_lshlrev_b32_e32 v192, 2, v64
	v_lshl_add_u64 v[68:69], v[68:69], 0, s[74:75]
	v_lshl_add_u64 v[96:97], v[68:69], 0, v[192:193]
	v_add_u32_e32 v70, 0xfffff800, v66
	v_mov_b32_e32 v68, s47
	v_mov_b32_e32 v69, s45
	v_cndmask_b32_e64 v69, v68, v69, s[40:41]
	v_mov_b32_e32 v68, s46
	v_mov_b32_e32 v71, s44
	v_cndmask_b32_e64 v66, v70, v66, s[40:41]
	v_cndmask_b32_e64 v70, 20, 23, s[40:41]
	v_cndmask_b32_e64 v68, v68, v71, s[40:41]
	v_lshlrev_b64 v[70:71], v70, s[28:29]
	v_lshl_add_u64 v[68:69], v[68:69], 0, v[70:71]
	v_lshlrev_b64 v[66:67], 12, v[66:67]
	v_lshl_add_u64 v[66:67], v[68:69], 0, v[66:67]
	v_lshl_add_u64 v[106:107], v[66:67], 0, s[74:75]
	v_bfe_u32 v66, v116, 3, 3
	v_xor_b32_e32 v68, v66, v116
	v_lshlrev_b32_e32 v66, 12, v66
	v_mov_b32_e32 v67, v193
	v_lshlrev_b32_e32 v68, 4, v68
	v_lshl_add_u64 v[70:71], v[96:97], 0, v[66:67]
	v_and_b32_e32 v68, 0x70, v68
	v_mov_b32_e32 v69, v193
	v_lshl_add_u64 v[112:113], v[70:71], 0, v[68:69]
	v_lshrrev_b32_e32 v70, 3, v117
	v_xor_b32_e32 v72, v70, v116
	v_lshlrev_b32_e32 v70, 12, v70
	v_mov_b32_e32 v71, v193
	v_lshlrev_b32_e32 v72, 4, v72
	v_lshl_add_u64 v[74:75], v[96:97], 0, v[70:71]
	v_and_b32_e32 v72, 0x70, v72
	v_lshl_add_u64 v[108:109], v[74:75], 0, v[72:73]
	v_lshrrev_b32_e32 v74, 3, v120
	v_xor_b32_e32 v76, v74, v116
	v_lshlrev_b32_e32 v74, 12, v74
	v_mov_b32_e32 v75, v193
	v_lshlrev_b32_e32 v76, 4, v76
	v_lshl_add_u64 v[78:79], v[96:97], 0, v[74:75]
	v_and_b32_e32 v76, 0x70, v76
	v_lshl_add_u64 v[100:101], v[78:79], 0, v[76:77]
	v_lshrrev_b32_e32 v78, 3, v121
	v_xor_b32_e32 v82, v78, v116
	v_bitop3_b32 v116, v119, v116, 7 bitop3:0x78
	v_lshl_add_u32 v150, v116, 4, v122
	ds_write_b128 v150, v[48:51]
	v_bitop3_b32 v48, v119, v123, 2 bitop3:0x36
	v_lshl_add_u32 v151, v48, 4, v122
	v_bitop3_b32 v48, v119, v123, 4 bitop3:0x36
	v_lshl_add_u32 v153, v48, 4, v122
	v_bitop3_b32 v48, v119, v123, 6 bitop3:0x36
	v_lshl_add_u64 v[106:107], v[106:107], 0, v[192:193]
	v_lshl_add_u32 v154, v48, 4, v122
	ds_write_b128 v151, v[52:55]
	ds_write_b128 v153, v[56:59]
	ds_write_b128 v154, v[60:63]
	ds_write_b128 v150, v[32:35] offset:4096
	ds_write_b128 v151, v[36:39] offset:4096
	ds_write_b128 v153, v[40:43] offset:4096
	ds_write_b128 v154, v[44:47] offset:4096
	v_lshl_add_u64 v[32:33], v[106:107], 0, v[66:67]
	v_lshl_add_u64 v[144:145], v[32:33], 0, v[68:69]
	v_lshl_add_u64 v[32:33], v[106:107], 0, v[70:71]
	v_lshlrev_b32_e32 v78, 12, v78
	v_mov_b32_e32 v79, v193
	v_lshlrev_b32_e32 v82, 4, v82
	v_lshl_add_u64 v[140:141], v[32:33], 0, v[72:73]
	v_lshl_add_u64 v[32:33], v[106:107], 0, v[74:75]
	v_and_b32_e32 v82, 0x70, v82
	v_lshl_add_u64 v[136:137], v[32:33], 0, v[76:77]
	v_lshl_add_u64 v[32:33], v[106:107], 0, v[78:79]
	v_lshl_add_u64 v[132:133], v[32:33], 0, v[82:83]
	v_lshl_add_u64 v[32:33], v[106:107], 0, v[84:85]
	v_lshl_add_u64 v[64:65], s[4:5], 0, v[192:193]
	v_lshl_add_u64 v[80:81], v[96:97], 0, v[78:79]
	v_lshl_add_u64 v[86:87], v[96:97], 0, v[84:85]
	v_lshl_add_u64 v[94:95], v[96:97], 0, v[90:91]
	v_lshl_add_u64 v[104:105], v[96:97], 0, v[98:99]
	v_lshl_add_u64 v[114:115], v[96:97], 0, v[110:111]
	v_lshlrev_b32_e32 v96, 4, v126
	v_lshl_add_u64 v[128:129], v[32:33], 0, v[88:89]
	v_lshl_add_u64 v[32:33], v[106:107], 0, v[90:91]
; template <int TJ>
; DI void outproj_tile(const Params& p, int l, char* smem, int b, int trow0, int n0) {
;     ...
;     float4 xo[2][4 * TJ];
; #pragma unroll
;     for (int i = 0; i < 2; ++i)
; #pragma unroll
;         for (int it = 0; it < 4 * TJ; ++it) {
;             const int c = lane + 64 * it, row = c >> 3, f = 32 * i + 4 * ((c & 7) ^ (row & 7));
;             xo[i][it] = *(const float4*)(xs + (size_t)row * D + f);
;         }
; #pragma unroll
;     for (int i = 0; i < 2; ++i) {
; #pragma unroll
;         for (int j = 0; j < TJ; ++j)
; #pragma unroll
;             for (int q = 0; q < 4; ++q) {
;                 const int row = 32 * j + r, c16 = 2 * q + h;
;                 float4 y; y.x = acc[i][j][4 * q]; y.y = acc[i][j][4 * q + 1]; y.z = acc[i][j][4 * q + 2]; y.w = acc[i][j][4 * q + 3];
;                 *(float4*)(sb + row * 128 + ((c16 ^ (row & 7)) << 4)) = y;
;             }
; #pragma unroll
;         for (int it = 0; it < 4 * TJ; ++it) {
;             const int c = lane + 64 * it, row = c >> 3, f = 32 * i + 4 * ((c & 7) ^ (row & 7));
;             const float4 y = *(const float4*)(sb + c * 16);
;             const float4 g4 = *(const float4*)(gt + f);
;             float4 o;
;             o.x = xo[i][it].x + g4.x * y.x; o.y = xo[i][it].y + g4.y * y.y; o.z = xo[i][it].z + g4.z * y.z; o.w = xo[i][it].w + g4.w * y.w;
;             *(float4*)(xd + (size_t)row * D + f) = o;
;         }
	v_lshl_add_u64 v[64:65], v[64:65], 0, s[16:17]
	v_and_b32_e32 v96, 0x70, v96
	v_mov_b32_e32 v97, v193
	v_lshl_add_u64 v[124:125], v[32:33], 0, v[92:93]
	v_lshl_add_u64 v[32:33], v[106:107], 0, v[98:99]
	v_lshl_add_u64 v[80:81], v[80:81], 0, v[82:83]
	v_lshl_add_u64 v[86:87], v[86:87], 0, v[88:89]
	v_lshl_add_u64 v[94:95], v[94:95], 0, v[92:93]
	v_lshl_add_u64 v[104:105], v[104:105], 0, v[102:103]
	v_lshl_add_u64 v[114:115], v[114:115], 0, v[96:97]
	v_lshl_add_u64 v[146:147], v[64:65], 0, v[68:69]
	v_lshl_add_u64 v[120:121], v[32:33], 0, v[102:103]
	v_lshl_add_u64 v[32:33], v[106:107], 0, v[110:111]
	v_lshl_add_u64 v[142:143], v[64:65], 0, v[72:73]
	v_lshl_add_u64 v[138:139], v[64:65], 0, v[76:77]
	v_lshl_add_u64 v[134:135], v[64:65], 0, v[82:83]
	v_lshl_add_u64 v[130:131], v[64:65], 0, v[88:89]
	v_lshl_add_u64 v[126:127], v[64:65], 0, v[92:93]
	v_lshl_add_u64 v[122:123], v[64:65], 0, v[102:103]
	v_lshl_add_u64 v[118:119], v[64:65], 0, v[96:97]
	v_lshl_add_u64 v[116:117], v[32:33], 0, v[96:97]
	global_load_dwordx4 v[60:63], v[114:115], off
	global_load_dwordx4 v[32:35], v[114:115], off offset:128
	global_load_dwordx4 v[64:67], v[104:105], off
	global_load_dwordx4 v[36:39], v[104:105], off offset:128
	global_load_dwordx4 v[68:71], v[94:95], off
	global_load_dwordx4 v[40:43], v[94:95], off offset:128
	global_load_dwordx4 v[76:79], v[86:87], off
	global_load_dwordx4 v[44:47], v[86:87], off offset:128
	s_nop 0
	global_load_dwordx4 v[84:87], v[80:81], off
	ds_read_b128 v[88:91], v157
	global_load_dwordx4 v[48:51], v[80:81], off offset:128
	global_load_dwordx4 v[92:95], v[100:101], off
	ds_read_b128 v[96:99], v158
	ds_read_b128 v[80:83], v156
	global_load_dwordx4 v[52:55], v[100:101], off offset:128
	s_nop 0
	global_load_dwordx4 v[100:103], v[108:109], off
	ds_read_b128 v[104:107], v159
	ds_read_b128 v[72:75], v152
	global_load_dwordx4 v[56:59], v[108:109], off offset:128
	s_nop 0
	global_load_dwordx4 v[108:111], v[112:113], off
	global_load_dwordx4 v[164:167], v[146:147], off
	global_load_dwordx4 v[168:171], v[146:147], off offset:128
	ds_read_b128 v[160:163], v155
	global_load_dwordx4 v[112:115], v[112:113], off offset:128
	s_mov_b64 s[4:5], 0
	s_waitcnt vmcnt(0) lgkmcnt(0)
	v_pk_fma_f32 v[108:109], v[160:161], v[164:165], v[108:109]
	v_pk_fma_f32 v[110:111], v[162:163], v[166:167], v[110:111]
	global_store_dwordx4 v[144:145], v[108:111], off
	v_pk_fma_f32 v[100:101], v[104:105], v[164:165], v[100:101]
	v_pk_fma_f32 v[102:103], v[106:107], v[166:167], v[102:103]
	global_store_dwordx4 v[140:141], v[100:103], off
	v_pk_fma_f32 v[92:93], v[96:97], v[164:165], v[92:93]
	v_pk_fma_f32 v[94:95], v[98:99], v[166:167], v[94:95]
	global_store_dwordx4 v[136:137], v[92:95], off
	v_pk_fma_f32 v[84:85], v[88:89], v[164:165], v[84:85]
	v_pk_fma_f32 v[86:87], v[90:91], v[166:167], v[86:87]
	global_store_dwordx4 v[132:133], v[84:87], off
	v_pk_fma_f32 v[76:77], v[80:81], v[164:165], v[76:77]
	v_pk_fma_f32 v[78:79], v[82:83], v[166:167], v[78:79]
	global_store_dwordx4 v[128:129], v[76:79], off
	v_pk_fma_f32 v[68:69], v[72:73], v[164:165], v[68:69]
	v_pk_fma_f32 v[70:71], v[74:75], v[166:167], v[70:71]
	global_store_dwordx4 v[124:125], v[68:71], off
	s_nop 1
	ds_read_b128 v[68:71], v149
	s_waitcnt lgkmcnt(0)
	v_pk_fma_f32 v[64:65], v[68:69], v[164:165], v[64:65]
	v_pk_fma_f32 v[66:67], v[70:71], v[166:167], v[66:67]
	global_store_dwordx4 v[120:121], v[64:67], off
	s_nop 1
	ds_read_b128 v[64:67], v148
	s_waitcnt lgkmcnt(0)
	v_pk_fma_f32 v[60:61], v[64:65], v[164:165], v[60:61]
	v_pk_fma_f32 v[62:63], v[66:67], v[166:167], v[62:63]
	global_store_dwordx4 v[116:117], v[60:63], off
	ds_write_b128 v150, v[16:19]
	ds_write_b128 v151, v[20:23]
	ds_write_b128 v153, v[24:27]
	ds_write_b128 v154, v[28:31]
	ds_write_b128 v150, v[0:3] offset:4096
	ds_write_b128 v151, v[4:7] offset:4096
	ds_write_b128 v153, v[8:11] offset:4096
	ds_write_b128 v154, v[12:15] offset:4096
	ds_read_b128 v[0:3], v155
	s_waitcnt lgkmcnt(0)
	v_pk_fma_f32 v[0:1], v[0:1], v[168:169], v[112:113]
	v_pk_fma_f32 v[2:3], v[2:3], v[170:171], v[114:115]
	global_store_dwordx4 v[144:145], v[0:3], off offset:128
	s_nop 1
	ds_read_b128 v[0:3], v159
	s_waitcnt lgkmcnt(0)
	v_pk_fma_f32 v[0:1], v[0:1], v[168:169], v[56:57]
	v_pk_fma_f32 v[2:3], v[2:3], v[170:171], v[58:59]
	global_store_dwordx4 v[140:141], v[0:3], off offset:128
	s_nop 1
	ds_read_b128 v[0:3], v158
	s_waitcnt lgkmcnt(0)
	v_pk_fma_f32 v[0:1], v[0:1], v[168:169], v[52:53]
	v_pk_fma_f32 v[2:3], v[2:3], v[170:171], v[54:55]
	global_store_dwordx4 v[136:137], v[0:3], off offset:128
	s_nop 1
	ds_read_b128 v[0:3], v157
	s_waitcnt lgkmcnt(0)
	v_pk_fma_f32 v[0:1], v[0:1], v[168:169], v[48:49]
	v_pk_fma_f32 v[2:3], v[2:3], v[170:171], v[50:51]
	global_store_dwordx4 v[132:133], v[0:3], off offset:128
	s_nop 1
	ds_read_b128 v[0:3], v156
	s_waitcnt lgkmcnt(0)
	v_pk_fma_f32 v[0:1], v[0:1], v[168:169], v[44:45]
	v_pk_fma_f32 v[2:3], v[2:3], v[170:171], v[46:47]
	global_store_dwordx4 v[128:129], v[0:3], off offset:128
	s_nop 1
	ds_read_b128 v[0:3], v152
	s_waitcnt lgkmcnt(0)
	v_pk_fma_f32 v[0:1], v[0:1], v[168:169], v[40:41]
	v_pk_fma_f32 v[2:3], v[2:3], v[170:171], v[42:43]
	global_store_dwordx4 v[124:125], v[0:3], off offset:128
	s_nop 1
	ds_read_b128 v[0:3], v149
	s_waitcnt lgkmcnt(0)
	v_pk_fma_f32 v[0:1], v[0:1], v[168:169], v[36:37]
	v_pk_fma_f32 v[2:3], v[2:3], v[170:171], v[38:39]
	global_store_dwordx4 v[120:121], v[0:3], off offset:128
	s_nop 1
	ds_read_b128 v[0:3], v148
	s_waitcnt lgkmcnt(0)
	v_pk_fma_f32 v[0:1], v[0:1], v[168:169], v[32:33]
	v_pk_fma_f32 v[2:3], v[2:3], v[170:171], v[34:35]
	global_store_dwordx4 v[116:117], v[0:3], off offset:128
	s_nop 1
	s_cbranch_vccnz .LBB0_52
